# final LN: hoist gamma/beta + next-row prefetch; spatial: prefetch row stats for next unit, gamma/beta via LDS, counted waits
# speedup vs baseline: 1.0091x; 1.0070x over previous
; #define SP_LOADV(u_) do { const int c_ = (u_) >> 4, g_ = (u_) & 15; \
;         _Pragma("unroll") for (int it = 0; it < 8; ++it) { const int X = tid + 512 * it, s_ = X >> 5, c8 = X & 31; \
;             vr[it] = *(const u32x4*)(V + (size_t)(c_ * 128 + s_) * EI + g_ * 256 + c8 * 8); } } while (0)
; __device__ void phase_spatial(const Params& p, unsigned char* shm) {
;     ...
;     u32x4 vr[8]; float bsv[8]; int gprev = -1;
;     ...
;     int unit = blockIdx.x;
;     if (unit < 5120) SP_LOADV(unit);
;     for (; unit < 5120; unit += gridDim.x) {
;         const int c = unit >> 4, g = unit & 15;
;         if (g != gprev) {
; #pragma unroll
;             for (int it = 0; it < 4; ++it) { const int X = tid + 512 * it, t = X >> 4, c16 = X & 15;
;                 *(u32x4*)(Wl + t * 136 + c16 * 8) = *(const u32x4*)(WSB + (size_t)g * 16384 + t * 128 + c16 * 8); }
; #pragma unroll
;             for (int nt = 0; nt < 8; ++nt) bsv[nt] = bs[g * 128 + 16 * nt + fr];
;             gprev = g;
;         }
; #pragma unroll
;         for (int it = 0; it < 8; ++it) { const int X = tid + 512 * it, s = X >> 5, c8 = X & 31, row = c * 128 + s, col = g * 256 + c8 * 8;
;             const u32x4 w = vr[it];
;             const float mu = st[(size_t)row * 2], rs = st[(size_t)row * 2 + 1];
;             const f32x4 ga = *(const f32x4*)(gam + col), gb = *(const f32x4*)(gam + col + 4), ba = *(const f32x4*)(bet + col), bb = *(const f32x4*)(bet + col + 4);
.LBB0_285:
	s_cmpk_gt_i32 s2, 0x13ff
	s_cbranch_scc1 .LBB0_294
	v_lshlrev_b32_e32 v0, 3, v136
	v_and_b32_e32 v32, 0xf8, v0
	v_add_u32_e32 v0, 0xa00, v136
	v_lshrrev_b32_e32 v163, 5, v0
	v_add_u32_e32 v0, 0xe00, v136
	s_add_u32 s6, s26, 0x3f7a0000
	v_lshrrev_b32_e32 v164, 5, v0
	v_lshlrev_b32_e32 v0, 4, v136
	s_addc_u32 s7, s27, 0
	v_mov_b32_e32 v81, 0
	v_and_b32_e32 v80, 0xf0, v0
	s_add_u32 s0, s26, 0x14000000
	v_lshl_add_u64 v[0:1], s[26:27], 0, v[80:81]
	s_mov_b64 s[14:15], 0x36000000
	s_addc_u32 s1, s27, 0
	v_lshl_add_u64 v[82:83], v[0:1], 0, s[14:15]
	v_lshrrev_b32_e32 v0, 1, v136
	s_add_i32 s8, 0, 0x8800
	v_bfe_u32 v3, v136, 4, 2
	v_and_b32_e32 v34, 0x1e0, v0
	v_bfe_u32 v0, v136, 2, 2
	s_cmp_lg_u32 s8, -1
	v_lshl_or_b32 v39, v3, 3, v0
	v_lshlrev_b32_e32 v0, 2, v136
	s_cselect_b32 s8, s8, 0
	s_lshl_b32 s14, s2, 9
	v_add_u32_e32 v4, 0x200, v136
	v_add_u32_e32 v35, 0, v80
	v_lshlrev_b32_e32 v80, 1, v32
	v_and_or_b32 v0, v0, 12, v34
	s_and_b32 s14, s14, 0x1e00
	v_lshl_add_u64 v[84:85], s[0:1], 0, v[80:81]
	v_lshlrev_b32_e32 v41, 1, v0
	v_lshrrev_b32_e32 v0, 4, v4
	v_or_b32_e32 v62, 0x400, v136
	s_add_u32 s0, s0, s14
	v_lshlrev_b32_e32 v40, 7, v0
	v_mul_u32_u24_e32 v61, 0x110, v0
	v_lshrrev_b32_e32 v0, 4, v62
	s_addc_u32 s1, s1, 0
	v_lshlrev_b32_e32 v42, 7, v0
	v_mul_u32_u24_e32 v63, 0x110, v0
	v_lshl_add_u64 v[0:1], s[0:1], 0, v[80:81]
	s_lshl_b32 s0, s2, 3
	v_lshrrev_b32_e32 v2, 4, v136
	s_and_b32 s1, s0, 0xffffff80
	v_lshlrev_b32_e32 v38, 7, v2
	v_mul_u32_u24_e32 v60, 0x110, v2
	v_add_u32_e32 v2, s1, v164
	v_lshlrev_b32_e32 v36, 2, v3
	v_lshl_add_u32 v43, v3, 4, 0
	v_ashrrev_i32_e32 v3, 31, v2
	v_lshrrev_b32_e32 v160, 5, v136
	v_lshlrev_b64 v[2:3], 13, v[2:3]
	v_lshl_add_u64 v[44:45], v[0:1], 0, v[2:3]
	v_or_b32_e32 v2, s1, v160
	v_lshrrev_b32_e32 v161, 5, v4
	v_or_b32_e32 v4, 0x60, v2
	v_ashrrev_i32_e32 v5, 31, v4
	v_lshlrev_b64 v[4:5], 13, v[4:5]
	v_lshl_add_u64 v[46:47], v[0:1], 0, v[4:5]
	v_or_b32_e32 v4, s1, v163
	v_ashrrev_i32_e32 v5, 31, v4
	v_lshlrev_b64 v[4:5], 13, v[4:5]
	v_lshl_add_u64 v[48:49], v[0:1], 0, v[4:5]
	v_or_b32_e32 v4, 64, v2
	v_add_u32_e32 v33, 0x600, v136
	v_ashrrev_i32_e32 v5, 31, v4
	v_lshrrev_b32_e32 v162, 5, v33
	v_lshlrev_b64 v[4:5], 13, v[4:5]
	v_lshl_add_u64 v[50:51], v[0:1], 0, v[4:5]
	v_or_b32_e32 v4, s1, v162
	v_ashrrev_i32_e32 v5, 31, v4
	v_lshlrev_b64 v[4:5], 13, v[4:5]
	v_lshl_add_u64 v[52:53], v[0:1], 0, v[4:5]
	v_or_b32_e32 v4, 32, v2
	v_ashrrev_i32_e32 v5, 31, v4
	v_lshlrev_b64 v[4:5], 13, v[4:5]
	v_lshl_add_u64 v[54:55], v[0:1], 0, v[4:5]
	v_or_b32_e32 v4, s1, v161
	v_ashrrev_i32_e32 v3, 31, v2
	v_ashrrev_i32_e32 v5, 31, v4
	v_lshlrev_b64 v[2:3], 13, v[2:3]
	v_lshlrev_b64 v[4:5], 13, v[4:5]
	v_lshl_add_u64 v[58:59], v[0:1], 0, v[2:3]
	v_lshl_add_u64 v[56:57], v[0:1], 0, v[4:5]
	global_load_dwordx4 v[0:3], v[58:59], off
	global_load_dwordx4 v[4:7], v[56:57], off
	global_load_dwordx4 v[8:11], v[54:55], off
	s_waitcnt lgkmcnt(0)
	global_load_dwordx4 v[12:15], v[52:53], off
	global_load_dwordx4 v[16:19], v[50:51], off
	global_load_dwordx4 v[20:23], v[48:49], off
	global_load_dwordx4 v[24:27], v[46:47], off
	global_load_dwordx4 v[28:31], v[44:45], off
	v_and_b32_e32 v137, 15, v136
	v_lshrrev_b32_e32 v33, 4, v33
	s_movk_i32 s1, 0x210
	v_mov_b32_e32 v46, 0x8400
	v_mul_u32_u24_e32 v39, 0x210, v39
	v_lshrrev_b32_e32 v171, 5, v62
	v_add_u32_e32 v37, 0, v80
	v_lshlrev_b32_e32 v44, 7, v33
	v_mul_u32_u24_e32 v33, 0x110, v33
	v_mul_u32_u24_e32 v45, 0x210, v160
	v_mad_u32_u24 v46, v160, s1, v46
	v_mul_u32_u24_e32 v47, 0x210, v163
	v_mul_u32_u24_e32 v48, 0x210, v164
	v_add3_u32 v167, v41, s8, v39
	v_mul_u32_u24_e32 v39, 0x110, v137
	v_mul_u32_u24_e32 v41, 0x210, v161
	v_mul_u32_u24_e32 v49, 0x210, v171
	v_mul_u32_u24_e32 v50, 0x210, v162
	s_add_i32 s1, s2, s30
	s_mov_b32 s9, 0
	s_mov_b32 s3, -1
	v_or_b32_e32 v165, 64, v160
	v_or_b32_e32 v166, 0x60, v160
	v_add_u32_e32 v168, 0x4200, v167
	v_add_u32_e32 v169, 0x8400, v167
	v_add_u32_e32 v170, 0xc600, v167
	s_lshl_b32 s74, s30, 3
	s_lshl_b32 s75, s1, 8
	s_lshl_b32 s76, s30, 8
	v_lshlrev_b32_e32 v86, 1, v38
	v_add_u32_e32 v172, v35, v60
	v_lshlrev_b32_e32 v88, 1, v40
	v_add_u32_e32 v173, v35, v61
	v_lshlrev_b32_e32 v90, 1, v42
	v_add_u32_e32 v174, v35, v63
	v_lshlrev_b32_e32 v92, 1, v44
	v_add_u32_e32 v175, v35, v33
	v_lshlrev_b32_e32 v176, 2, v32
	v_add_u32_e32 v177, v37, v45
	v_add_u32_e32 v178, v37, v41
	v_add_u32_e32 v179, v37, v49
	v_add_u32_e32 v180, v37, v50
	v_add_u32_e32 v181, v37, v46
	v_add_u32_e32 v182, v37, v47
	v_add_u32_e32 v183, v37, v48
	v_lshlrev_b32_e32 v80, 1, v34
	v_lshlrev_b32_e32 v94, 1, v36
	s_mov_b64 s[14:15], 0x20000
	s_mov_b32 s77, 0x20000
	s_mov_b64 s[18:19], 0x20020
	s_mov_b64 s[20:21], 0x40000
	s_mov_b32 s78, 0x40000
	s_mov_b64 s[22:23], 0x40020
	s_mov_b64 s[24:25], 0x60000
	s_mov_b32 s79, 0x60000
	s_mov_b64 s[52:53], 0x60020
	s_mov_b64 s[54:55], 0x80000
	s_mov_b32 s80, 0x80000
	s_mov_b64 s[56:57], 0x80020
	s_mov_b64 s[58:59], 0xa0000
	s_mov_b32 s81, 0xa0000
	s_mov_b64 s[60:61], 0xa0020
	s_mov_b64 s[62:63], 0xc0000
	s_mov_b32 s82, 0xc0000
	s_mov_b64 s[64:65], 0xc0020
	s_mov_b64 s[66:67], 0xe0000
	s_mov_b64 s[68:69], 0xe0020
	v_add_u32_e32 v184, v43, v39
	s_mov_b32 s83, s2
	s_and_b32 s8, s0, 0xffffff80
	v_or_b32_e32 v238, s8, v160
	v_ashrrev_i32_e32 v239, 31, v238
	v_lshl_add_u64 v[238:239], v[238:239], 3, s[6:7]
	global_load_dwordx2 v[238:239], v[238:239], off
	v_or_b32_e32 v240, s8, v161
	v_ashrrev_i32_e32 v241, 31, v240
	v_lshl_add_u64 v[240:241], v[240:241], 3, s[6:7]
	global_load_dwordx2 v[240:241], v[240:241], off
	v_or_b32_e32 v242, s8, v171
	v_ashrrev_i32_e32 v243, 31, v242
	v_lshl_add_u64 v[242:243], v[242:243], 3, s[6:7]
	global_load_dwordx2 v[242:243], v[242:243], off
	v_or_b32_e32 v244, s8, v162
	v_ashrrev_i32_e32 v245, 31, v244
	v_lshl_add_u64 v[244:245], v[244:245], 3, s[6:7]
	global_load_dwordx2 v[244:245], v[244:245], off
	v_or_b32_e32 v248, s8, v165
	v_ashrrev_i32_e32 v249, 31, v248
	v_lshl_add_u64 v[248:249], v[248:249], 3, s[6:7]
	global_load_dwordx2 v[248:249], v[248:249], off
	v_or_b32_e32 v250, s8, v163
	v_ashrrev_i32_e32 v251, 31, v250
	v_lshl_add_u64 v[250:251], v[250:251], 3, s[6:7]
	global_load_dwordx2 v[250:251], v[250:251], off
	v_or_b32_e32 v252, s8, v166
	v_ashrrev_i32_e32 v253, 31, v252
	v_lshl_add_u64 v[252:253], v[252:253], 3, s[6:7]
	global_load_dwordx2 v[252:253], v[252:253], off
	v_or_b32_e32 v254, s8, v164
	v_ashrrev_i32_e32 v255, 31, v254
	v_lshl_add_u64 v[254:255], v[254:255], 3, s[6:7]
	global_load_dwordx2 v[254:255], v[254:255], off
	s_and_b32 s99, s2, 15
	s_lshl_b32 s99, s99, 10
	v_or_b32_e32 v36, s99, v176
	global_load_dwordx4 v[40:43], v36, s[10:11]
	global_load_dwordx4 v[44:47], v36, s[12:13]
	global_load_dwordx4 v[32:35], v36, s[10:11] offset:16
	global_load_dwordx4 v[48:51], v36, s[12:13] offset:16
	s_mov_b32 s98, 0x19000
	v_lshl_add_u32 v52, v136, 4, s98
	s_waitcnt vmcnt(0)
	ds_write_b128 v52, v[40:43]
	ds_write_b128 v52, v[44:47] offset:8192
	ds_write_b128 v52, v[32:35] offset:16384
	ds_write_b128 v52, v[48:51] offset:24576
	s_waitcnt lgkmcnt(0)
	s_branch .LBB0_288

; DI unsigned cvt_pk_bf16(float lo, float hi) { unsigned r; asm("v_cvt_pk_bf16_f32 %0, %1, %2" : "=v"(r) : "v"(lo), "v"(hi)); return r; }
; __device__ void phase_spatial(const Params& p, unsigned char* shm) {
;     ...
;         for (int it = 0; it < 8; ++it) { const int X = tid + 512 * it, s = X >> 5, c8 = X & 31, row = c * 128 + s, col = g * 256 + c8 * 8;
;             const u32x4 w = vr[it];
;             const float mu = st[(size_t)row * 2], rs = st[(size_t)row * 2 + 1];
;             const f32x4 ga = *(const f32x4*)(gam + col), gb = *(const f32x4*)(gam + col + 4), ba = *(const f32x4*)(bet + col), bb = *(const f32x4*)(bet + col + 4);
;             u32x4 o;
;             o.x = cvt_pk_bf16((bflo(w.x) - mu) * rs * ga[0] + ba[0], (bfhi(w.x) - mu) * rs * ga[1] + ba[1]);
;             o.y = cvt_pk_bf16((bflo(w.y) - mu) * rs * ga[2] + ba[2], (bfhi(w.y) - mu) * rs * ga[3] + ba[3]);
;             o.z = cvt_pk_bf16((bflo(w.z) - mu) * rs * gb[0] + bb[0], (bfhi(w.z) - mu) * rs * gb[1] + bb[1]);
;             o.w = cvt_pk_bf16((bflo(w.w) - mu) * rs * gb[2] + bb[2], (bfhi(w.w) - mu) * rs * gb[3] + bb[3]);
;             *(u32x4*)(Vl + s * 264 + c8 * 8) = o; }
.LBB0_290:
	s_and_b32 s8, s0, 0xffffff80
	v_or_b32_e32 v32, s8, v160
	v_ashrrev_i32_e32 v33, 31, v32
	v_lshl_add_u64 v[32:33], v[32:33], 3, s[6:7]
	v_mov_b64 v[48:49], v[238:239]
	v_or_b32_e32 v32, s8, v161
	v_ashrrev_i32_e32 v33, 31, v32
	v_lshl_add_u64 v[32:33], v[32:33], 3, s[6:7]
	v_mov_b64 v[56:57], v[240:241]
	v_lshl_add_u32 v36, v136, 4, s98
	ds_read_b128 v[40:43], v36
	ds_read_b128 v[44:47], v36 offset:8192
	ds_read_b128 v[32:35], v36 offset:16384
	ds_read_b128 v[36:39], v36 offset:24576
	v_or_b32_e32 v50, s8, v171
	v_ashrrev_i32_e32 v51, 31, v50
	v_lshl_add_u64 v[50:51], v[50:51], 3, s[6:7]
	v_mov_b64 v[58:59], v[242:243]
	v_or_b32_e32 v50, s8, v162
	v_ashrrev_i32_e32 v51, 31, v50
	v_lshl_add_u64 v[50:51], v[50:51], 3, s[6:7]
	v_mov_b64 v[60:61], v[244:245]
	s_waitcnt vmcnt(16) lgkmcnt(0)
	v_lshlrev_b32_e32 v52, 16, v0
	v_and_b32_e32 v53, 0xffff0000, v0
	v_lshlrev_b32_e32 v54, 16, v1
	v_and_b32_e32 v55, 0xffff0000, v1
	v_lshlrev_b32_e32 v62, 16, v2
	v_and_b32_e32 v63, 0xffff0000, v2
	v_lshlrev_b32_e32 v64, 16, v3
	v_and_b32_e32 v65, 0xffff0000, v3
	v_lshlrev_b32_e32 v66, 16, v4
	v_and_b32_e32 v67, 0xffff0000, v4
	v_lshlrev_b32_e32 v68, 16, v5
	v_and_b32_e32 v69, 0xffff0000, v5
	v_lshlrev_b32_e32 v70, 16, v6
	v_and_b32_e32 v71, 0xffff0000, v6
	v_lshlrev_b32_e32 v72, 16, v7
	v_mov_b32_e32 v95, v81
	s_add_i32 s83, s83, s30
	s_mov_b64 s[72:73], -1
	v_sub_f32_e32 v50, v52, v48
	v_sub_f32_e32 v51, v53, v48
	v_sub_f32_e32 v52, v54, v48
	v_sub_f32_e32 v53, v55, v48
	v_sub_f32_e32 v54, v62, v48
	v_sub_f32_e32 v55, v63, v48
	v_sub_f32_e32 v62, v64, v48
	v_sub_f32_e32 v48, v65, v48
	v_sub_f32_e32 v63, v66, v56
	v_mul_f32_e32 v50, v49, v50
	v_mul_f32_e32 v51, v49, v51
	v_mul_f32_e32 v52, v49, v52
	v_mul_f32_e32 v53, v49, v53
	v_mul_f32_e32 v54, v49, v54
	v_mul_f32_e32 v55, v49, v55
	v_mul_f32_e32 v62, v49, v62
	v_mul_f32_e32 v48, v49, v48
	v_mul_f32_e32 v49, v57, v63
	v_sub_f32_e32 v64, v67, v56
	v_sub_f32_e32 v65, v68, v56
	v_sub_f32_e32 v66, v69, v56
	v_sub_f32_e32 v67, v70, v56
	v_sub_f32_e32 v68, v71, v56
	v_sub_f32_e32 v69, v72, v56
	v_fma_f32 v50, v50, v40, v44
	v_fma_f32 v51, v51, v41, v45
	v_fma_f32 v52, v52, v42, v46
	v_fma_f32 v53, v53, v43, v47
	v_fma_f32 v70, v40, v49, v44
	v_cvt_pk_bf16_f32 v49, v52, v53
	v_mul_f32_e32 v63, v57, v64
	v_mul_f32_e32 v64, v57, v65
	v_mul_f32_e32 v65, v57, v66
	v_mul_f32_e32 v66, v57, v67
	v_mul_f32_e32 v67, v57, v68
	v_mul_f32_e32 v68, v57, v69
	v_fma_f32 v54, v54, v32, v36
	v_fma_f32 v55, v55, v33, v37
	v_fma_f32 v62, v62, v34, v38
	v_fma_f32 v69, v48, v35, v39
	v_cvt_pk_bf16_f32 v48, v50, v51
	v_cvt_pk_bf16_f32 v50, v54, v55
	v_cvt_pk_bf16_f32 v51, v62, v69
	ds_write_b128 v177, v[48:51] offset:34816
	v_and_b32_e32 v49, 0xffff0000, v7
	v_sub_f32_e32 v49, v49, v56
	v_fma_f32 v48, v34, v68, v38
	v_mul_f32_e32 v49, v57, v49
	v_fma_f32 v49, v35, v49, v39
	v_cvt_pk_bf16_f32 v55, v48, v49
	v_lshlrev_b32_e32 v48, 16, v8
	v_sub_f32_e32 v48, v48, v58
	v_mul_f32_e32 v48, v59, v48
	v_fma_f32 v50, v40, v48, v44
	v_and_b32_e32 v48, 0xffff0000, v8
	v_sub_f32_e32 v48, v48, v58
	v_mul_f32_e32 v48, v59, v48
	v_fma_f32 v51, v41, v48, v45
	v_or_b32_e32 v48, s8, v165
	v_ashrrev_i32_e32 v49, 31, v48
	v_lshl_add_u64 v[48:49], v[48:49], 3, s[6:7]
	v_mov_b64 v[56:57], v[248:249]
	v_cvt_pk_bf16_f32 v48, v50, v51
	v_lshlrev_b32_e32 v49, 16, v9
	v_and_b32_e32 v50, 0xffff0000, v9
	v_sub_f32_e32 v49, v49, v58
	v_sub_f32_e32 v50, v50, v58
	v_mul_f32_e32 v49, v59, v49
	v_mul_f32_e32 v50, v59, v50
	v_fma_f32 v49, v42, v49, v46
	v_fma_f32 v50, v43, v50, v47
	v_cvt_pk_bf16_f32 v49, v49, v50
	v_lshlrev_b32_e32 v50, 16, v10
	v_and_b32_e32 v51, 0xffff0000, v10
	v_sub_f32_e32 v50, v50, v58
	v_sub_f32_e32 v51, v51, v58
	v_mul_f32_e32 v50, v59, v50
	v_mul_f32_e32 v51, v59, v51
	v_fma_f32 v50, v32, v50, v36
	v_fma_f32 v51, v33, v51, v37
	v_fma_f32 v63, v41, v63, v45
	v_cvt_pk_bf16_f32 v52, v70, v63
	v_cvt_pk_bf16_f32 v50, v50, v51
	v_lshlrev_b32_e32 v51, 16, v11
	v_fma_f32 v64, v42, v64, v46
	v_fma_f32 v65, v43, v65, v47
	v_fma_f32 v66, v32, v66, v36
	v_fma_f32 v67, v33, v67, v37
	v_cvt_pk_bf16_f32 v53, v64, v65
	v_cvt_pk_bf16_f32 v54, v66, v67
	ds_write_b128 v178, v[52:55] offset:34816
	v_sub_f32_e32 v51, v51, v58
	v_and_b32_e32 v52, 0xffff0000, v11
	v_mul_f32_e32 v51, v59, v51
	v_sub_f32_e32 v52, v52, v58
	v_fma_f32 v51, v34, v51, v38
	v_mul_f32_e32 v52, v59, v52
	v_fma_f32 v52, v35, v52, v39
	v_cvt_pk_bf16_f32 v51, v51, v52
	ds_write_b128 v179, v[48:51] offset:34816
	v_lshlrev_b32_e32 v48, 16, v12
	v_sub_f32_e32 v48, v48, v60
	v_mul_f32_e32 v48, v61, v48
	v_fma_f32 v50, v40, v48, v44
	v_or_b32_e32 v48, s8, v163
	v_ashrrev_i32_e32 v49, 31, v48
	v_lshl_add_u64 v[48:49], v[48:49], 3, s[6:7]
	v_mov_b64 v[58:59], v[250:251]
	v_and_b32_e32 v48, 0xffff0000, v12
	v_sub_f32_e32 v48, v48, v60
	v_mul_f32_e32 v48, v61, v48
	v_fma_f32 v48, v41, v48, v45
	v_cvt_pk_bf16_f32 v48, v50, v48
	v_lshlrev_b32_e32 v49, 16, v13
	v_and_b32_e32 v50, 0xffff0000, v13
	v_sub_f32_e32 v49, v49, v60
	v_sub_f32_e32 v50, v50, v60
	v_mul_f32_e32 v49, v61, v49
	v_mul_f32_e32 v50, v61, v50
	v_fma_f32 v49, v42, v49, v46
	v_fma_f32 v50, v43, v50, v47
	v_cvt_pk_bf16_f32 v49, v49, v50
	v_lshlrev_b32_e32 v50, 16, v14
	v_and_b32_e32 v51, 0xffff0000, v14
	v_sub_f32_e32 v50, v50, v60
	v_sub_f32_e32 v51, v51, v60
	v_mul_f32_e32 v50, v61, v50
	v_mul_f32_e32 v51, v61, v51
	v_fma_f32 v50, v32, v50, v36
	v_fma_f32 v51, v33, v51, v37
	v_cvt_pk_bf16_f32 v50, v50, v51
	v_lshlrev_b32_e32 v51, 16, v15
	v_sub_f32_e32 v51, v51, v60
	v_and_b32_e32 v52, 0xffff0000, v15
	v_mul_f32_e32 v51, v61, v51
	v_sub_f32_e32 v52, v52, v60
	v_fma_f32 v51, v34, v51, v38
	v_mul_f32_e32 v52, v61, v52
; DI unsigned cvt_pk_bf16(float lo, float hi) { unsigned r; asm("v_cvt_pk_bf16_f32 %0, %1, %2" : "=v"(r) : "v"(lo), "v"(hi)); return r; }
; __device__ void phase_spatial(const Params& p, unsigned char* shm) {
;     ...
;         for (int it = 0; it < 8; ++it) { const int X = tid + 512 * it, s = X >> 5, c8 = X & 31, row = c * 128 + s, col = g * 256 + c8 * 8;
;             const u32x4 w = vr[it];
;             const float mu = st[(size_t)row * 2], rs = st[(size_t)row * 2 + 1];
;             const f32x4 ga = *(const f32x4*)(gam + col), gb = *(const f32x4*)(gam + col + 4), ba = *(const f32x4*)(bet + col), bb = *(const f32x4*)(bet + col + 4);
;             u32x4 o;
;             o.x = cvt_pk_bf16((bflo(w.x) - mu) * rs * ga[0] + ba[0], (bfhi(w.x) - mu) * rs * ga[1] + ba[1]);
;             o.y = cvt_pk_bf16((bflo(w.y) - mu) * rs * ga[2] + ba[2], (bfhi(w.y) - mu) * rs * ga[3] + ba[3]);
;             o.z = cvt_pk_bf16((bflo(w.z) - mu) * rs * gb[0] + bb[0], (bfhi(w.z) - mu) * rs * gb[1] + bb[1]);
;             o.w = cvt_pk_bf16((bflo(w.w) - mu) * rs * gb[2] + bb[2], (bfhi(w.w) - mu) * rs * gb[3] + bb[3]);
;             *(u32x4*)(Vl + s * 264 + c8 * 8) = o; }
	v_fma_f32 v52, v35, v52, v39
	v_cvt_pk_bf16_f32 v51, v51, v52
	ds_write_b128 v180, v[48:51] offset:34816
	v_or_b32_e32 v48, s8, v166
	v_ashrrev_i32_e32 v49, 31, v48
	v_lshl_add_u64 v[48:49], v[48:49], 3, s[6:7]
	v_mov_b64 v[48:49], v[252:253]
	v_lshlrev_b32_e32 v52, 16, v16
	v_and_b32_e32 v53, 0xffff0000, v16
	v_sub_f32_e32 v52, v52, v56
	v_sub_f32_e32 v53, v53, v56
	v_mul_f32_e32 v52, v57, v52
	v_mul_f32_e32 v53, v57, v53
	v_fma_f32 v52, v40, v52, v44
	v_fma_f32 v53, v41, v53, v45
	v_cvt_pk_bf16_f32 v52, v52, v53
	v_lshlrev_b32_e32 v53, 16, v17
	v_and_b32_e32 v54, 0xffff0000, v17
	v_sub_f32_e32 v53, v53, v56
	v_sub_f32_e32 v54, v54, v56
	v_mul_f32_e32 v53, v57, v53
	v_mul_f32_e32 v54, v57, v54
	v_fma_f32 v53, v42, v53, v46
	v_fma_f32 v54, v43, v54, v47
	v_cvt_pk_bf16_f32 v53, v53, v54
	v_lshlrev_b32_e32 v54, 16, v18
	v_and_b32_e32 v55, 0xffff0000, v18
	v_sub_f32_e32 v54, v54, v56
	v_sub_f32_e32 v55, v55, v56
	v_mul_f32_e32 v54, v57, v54
	v_mul_f32_e32 v55, v57, v55
	v_fma_f32 v54, v32, v54, v36
	v_fma_f32 v55, v33, v55, v37
	v_cvt_pk_bf16_f32 v54, v54, v55
	v_lshlrev_b32_e32 v55, 16, v19
	v_sub_f32_e32 v55, v55, v56
	v_and_b32_e32 v60, 0xffff0000, v19
	v_mul_f32_e32 v55, v57, v55
	v_sub_f32_e32 v56, v60, v56
	v_fma_f32 v55, v34, v55, v38
	v_mul_f32_e32 v56, v57, v56
	v_fma_f32 v56, v35, v56, v39
	v_cvt_pk_bf16_f32 v55, v55, v56
	ds_write_b128 v181, v[52:55] offset:34816
	v_lshlrev_b32_e32 v52, 16, v20
	v_and_b32_e32 v53, 0xffff0000, v20
	v_and_b32_e32 v54, 0xffff0000, v21
	v_and_b32_e32 v55, 0xffff0000, v22
	v_and_b32_e32 v56, 0xffff0000, v23
	v_sub_f32_e32 v52, v52, v58
	v_sub_f32_e32 v53, v53, v58
	v_mul_f32_e32 v52, v59, v52
	v_mul_f32_e32 v53, v59, v53
	v_fma_f32 v52, v40, v52, v44
	v_fma_f32 v53, v41, v53, v45
	v_cvt_pk_bf16_f32 v52, v52, v53
	v_lshlrev_b32_e32 v53, 16, v21
	v_sub_f32_e32 v53, v53, v58
	v_sub_f32_e32 v54, v54, v58
	v_mul_f32_e32 v53, v59, v53
	v_mul_f32_e32 v54, v59, v54
	v_fma_f32 v53, v42, v53, v46
	v_fma_f32 v54, v43, v54, v47
	v_cvt_pk_bf16_f32 v53, v53, v54
	v_lshlrev_b32_e32 v54, 16, v22
	v_sub_f32_e32 v54, v54, v58
	v_sub_f32_e32 v55, v55, v58
	v_mul_f32_e32 v54, v59, v54
	v_mul_f32_e32 v55, v59, v55
	v_fma_f32 v54, v32, v54, v36
	v_fma_f32 v55, v33, v55, v37
	v_cvt_pk_bf16_f32 v54, v54, v55
	v_lshlrev_b32_e32 v55, 16, v23
	v_sub_f32_e32 v55, v55, v58
	v_add_u32_e32 v50, s8, v164
	v_mul_f32_e32 v55, v59, v55
	v_sub_f32_e32 v56, v56, v58
	v_ashrrev_i32_e32 v51, 31, v50
	v_fma_f32 v55, v34, v55, v38
	v_mul_f32_e32 v56, v59, v56
	v_lshl_add_u64 v[50:51], v[50:51], 3, s[6:7]
	v_fma_f32 v56, v35, v56, v39
	v_cvt_pk_bf16_f32 v55, v55, v56
	ds_write_b128 v182, v[52:55] offset:34816
	v_lshlrev_b32_e32 v52, 16, v24
	v_mov_b64 v[50:51], v[254:255]
	s_add_i32 s99, s0, s74
	s_and_b32 s99, s99, 0xffffff80
	v_or_b32_e32 v238, s99, v160
	v_ashrrev_i32_e32 v239, 31, v238
	v_lshl_add_u64 v[238:239], v[238:239], 3, s[6:7]
	global_load_dwordx2 v[238:239], v[238:239], off
	v_or_b32_e32 v240, s99, v161
	v_ashrrev_i32_e32 v241, 31, v240
	v_lshl_add_u64 v[240:241], v[240:241], 3, s[6:7]
	global_load_dwordx2 v[240:241], v[240:241], off
	v_or_b32_e32 v242, s99, v171
	v_ashrrev_i32_e32 v243, 31, v242
	v_lshl_add_u64 v[242:243], v[242:243], 3, s[6:7]
	global_load_dwordx2 v[242:243], v[242:243], off
	v_or_b32_e32 v244, s99, v162
	v_ashrrev_i32_e32 v245, 31, v244
	v_lshl_add_u64 v[244:245], v[244:245], 3, s[6:7]
	global_load_dwordx2 v[244:245], v[244:245], off
	v_or_b32_e32 v248, s99, v165
	v_ashrrev_i32_e32 v249, 31, v248
	v_lshl_add_u64 v[248:249], v[248:249], 3, s[6:7]
	global_load_dwordx2 v[248:249], v[248:249], off
	v_or_b32_e32 v250, s99, v163
	v_ashrrev_i32_e32 v251, 31, v250
	v_lshl_add_u64 v[250:251], v[250:251], 3, s[6:7]
	global_load_dwordx2 v[250:251], v[250:251], off
	v_or_b32_e32 v252, s99, v166
	v_ashrrev_i32_e32 v253, 31, v252
	v_lshl_add_u64 v[252:253], v[252:253], 3, s[6:7]
	global_load_dwordx2 v[252:253], v[252:253], off
	v_or_b32_e32 v254, s99, v164
	v_ashrrev_i32_e32 v255, 31, v254
	v_lshl_add_u64 v[254:255], v[254:255], 3, s[6:7]
	global_load_dwordx2 v[254:255], v[254:255], off
	v_sub_f32_e32 v52, v52, v48
	v_mul_f32_e32 v56, v49, v52
; DI unsigned cvt_pk_bf16(float lo, float hi) { unsigned r; asm("v_cvt_pk_bf16_f32 %0, %1, %2" : "=v"(r) : "v"(lo), "v"(hi)); return r; }
; #define SP_LOADV(u_) do { const int c_ = (u_) >> 4, g_ = (u_) & 15; \
;         _Pragma("unroll") for (int it = 0; it < 8; ++it) { const int X = tid + 512 * it, s_ = X >> 5, c8 = X & 31; \
;             vr[it] = *(const u32x4*)(V + (size_t)(c_ * 128 + s_) * EI + g_ * 256 + c8 * 8); } } while (0)
; __device__ void phase_spatial(const Params& p, unsigned char* shm) {
;     ...
;         for (int it = 0; it < 8; ++it) { const int X = tid + 512 * it, s = X >> 5, c8 = X & 31, row = c * 128 + s, col = g * 256 + c8 * 8;
;             const u32x4 w = vr[it];
;             const float mu = st[(size_t)row * 2], rs = st[(size_t)row * 2 + 1];
;             const f32x4 ga = *(const f32x4*)(gam + col), gb = *(const f32x4*)(gam + col + 4), ba = *(const f32x4*)(bet + col), bb = *(const f32x4*)(bet + col + 4);
;             u32x4 o;
;             o.x = cvt_pk_bf16((bflo(w.x) - mu) * rs * ga[0] + ba[0], (bfhi(w.x) - mu) * rs * ga[1] + ba[1]);
;             o.y = cvt_pk_bf16((bflo(w.y) - mu) * rs * ga[2] + ba[2], (bfhi(w.y) - mu) * rs * ga[3] + ba[3]);
;             o.z = cvt_pk_bf16((bflo(w.z) - mu) * rs * gb[0] + bb[0], (bfhi(w.z) - mu) * rs * gb[1] + bb[1]);
;             o.w = cvt_pk_bf16((bflo(w.w) - mu) * rs * gb[2] + bb[2], (bfhi(w.w) - mu) * rs * gb[3] + bb[3]);
;             *(u32x4*)(Vl + s * 264 + c8 * 8) = o; }
;         u32x2 gq[8][2];
;         bf16_t* gp0 = G + (size_t)(c * 128 + fr) * EI + g * 256 + 32 * wid + 4 * fq;
; #pragma unroll
;         for (int nt = 0; nt < 8; ++nt)
; #pragma unroll
;             for (int mt = 0; mt < 2; ++mt) gq[nt][mt] = *(const u32x2*)(gp0 + (size_t)(16 * nt) * EI + 16 * mt);
;         __syncthreads();
;         { const int nu = unit + (int)gridDim.x; if (nu < 5120) SP_LOADV(nu); }
	v_or_b32_e32 v52, s8, v137
	v_ashrrev_i32_e32 v53, 31, v52
	v_lshlrev_b64 v[52:53], 13, v[52:53]
	v_lshl_add_u64 v[52:53], s[26:27], 0, v[52:53]
	s_lshl_b32 s8, s1, 9
	v_lshl_add_u64 v[52:53], v[52:53], 0, s[8:9]
	v_lshl_add_u64 v[52:53], v[52:53], 0, v[80:81]
	v_lshl_add_u64 v[140:141], v[52:53], 0, v[94:95]
	v_add_co_u32_e32 v52, vcc, s77, v140
	global_load_dwordx2 v[146:147], v[140:141], off
	global_load_dwordx2 v[142:143], v[140:141], off offset:32
	v_addc_co_u32_e32 v53, vcc, 0, v141, vcc
	v_add_co_u32_e32 v54, vcc, s78, v140
	s_cmpk_gt_i32 s83, 0x13ff
	s_nop 0
	v_addc_co_u32_e32 v55, vcc, 0, v141, vcc
	global_load_dwordx2 v[134:135], v[52:53], off
	global_load_dwordx2 v[128:129], v[52:53], off offset:32
	global_load_dwordx2 v[122:123], v[54:55], off
	global_load_dwordx2 v[116:117], v[54:55], off offset:32
	v_add_co_u32_e32 v52, vcc, s79, v140
	s_cselect_b64 s[70:71], -1, 0
	s_nop 0
	v_addc_co_u32_e32 v53, vcc, 0, v141, vcc
	v_add_co_u32_e32 v54, vcc, s80, v140
	s_cmpk_lt_i32 s83, 0x1400
	s_nop 0
	v_addc_co_u32_e32 v55, vcc, 0, v141, vcc
	global_load_dwordx2 v[114:115], v[52:53], off
	global_load_dwordx2 v[112:113], v[52:53], off offset:32
	global_load_dwordx2 v[110:111], v[54:55], off
	global_load_dwordx2 v[108:109], v[54:55], off offset:32
	v_add_co_u32_e32 v52, vcc, s81, v140
	s_nop 1
	v_addc_co_u32_e32 v53, vcc, 0, v141, vcc
	v_add_co_u32_e32 v54, vcc, s82, v140
	s_nop 1
	v_addc_co_u32_e32 v55, vcc, 0, v141, vcc
	global_load_dwordx2 v[106:107], v[52:53], off
	global_load_dwordx2 v[104:105], v[52:53], off offset:32
	global_load_dwordx2 v[102:103], v[54:55], off
	global_load_dwordx2 v[100:101], v[54:55], off offset:32
	v_add_co_u32_e32 v52, vcc, 0xe0000, v140
	v_and_b32_e32 v54, 0xffff0000, v25
	s_nop 0
	v_addc_co_u32_e32 v53, vcc, 0, v141, vcc
	global_load_dwordx2 v[98:99], v[52:53], off
	global_load_dwordx2 v[96:97], v[52:53], off offset:32
	v_and_b32_e32 v53, 0xffff0000, v24
	v_sub_f32_e32 v53, v53, v48
	v_mul_f32_e32 v53, v49, v53
	v_fma_f32 v52, v40, v56, v44
	v_fma_f32 v53, v41, v53, v45
	v_cvt_pk_bf16_f32 v52, v52, v53
	v_lshlrev_b32_e32 v53, 16, v25
	v_sub_f32_e32 v53, v53, v48
	v_sub_f32_e32 v54, v54, v48
	v_mul_f32_e32 v53, v49, v53
	v_mul_f32_e32 v54, v49, v54
	v_fma_f32 v53, v42, v53, v46
	v_fma_f32 v54, v43, v54, v47
	v_cvt_pk_bf16_f32 v53, v53, v54
	v_lshlrev_b32_e32 v54, 16, v26
	v_and_b32_e32 v55, 0xffff0000, v26
	v_sub_f32_e32 v54, v54, v48
	v_sub_f32_e32 v55, v55, v48
	v_mul_f32_e32 v54, v49, v54
	v_mul_f32_e32 v55, v49, v55
	v_fma_f32 v54, v32, v54, v36
	v_fma_f32 v55, v33, v55, v37
	v_cvt_pk_bf16_f32 v54, v54, v55
	v_lshlrev_b32_e32 v55, 16, v27
	v_and_b32_e32 v56, 0xffff0000, v27
	v_sub_f32_e32 v55, v55, v48
	v_sub_f32_e32 v48, v56, v48
	v_mul_f32_e32 v55, v49, v55
	v_mul_f32_e32 v48, v49, v48
	v_fma_f32 v55, v34, v55, v38
	v_fma_f32 v48, v35, v48, v39
	v_cvt_pk_bf16_f32 v55, v55, v48
	v_lshlrev_b32_e32 v48, 16, v28
	v_sub_f32_e32 v48, v48, v50
	v_mul_f32_e32 v48, v51, v48
	v_fma_f32 v40, v40, v48, v44
	v_and_b32_e32 v44, 0xffff0000, v28
	v_sub_f32_e32 v44, v44, v50
	v_mul_f32_e32 v44, v51, v44
	v_fma_f32 v41, v41, v44, v45
	v_cvt_pk_bf16_f32 v40, v40, v41
	v_lshlrev_b32_e32 v41, 16, v29
	v_sub_f32_e32 v41, v41, v50
	v_mul_f32_e32 v41, v51, v41
	v_fma_f32 v41, v42, v41, v46
	v_and_b32_e32 v42, 0xffff0000, v29
	v_sub_f32_e32 v42, v42, v50
	v_mul_f32_e32 v42, v51, v42
	v_fmac_f32_e32 v47, v43, v42
	v_lshlrev_b32_e32 v42, 16, v30
	v_sub_f32_e32 v42, v42, v50
	v_mul_f32_e32 v42, v51, v42
	v_fma_f32 v32, v32, v42, v36
	v_and_b32_e32 v36, 0xffff0000, v30
	v_sub_f32_e32 v36, v36, v50
	v_mul_f32_e32 v36, v51, v36
	v_fma_f32 v33, v33, v36, v37
	v_cvt_pk_bf16_f32 v42, v32, v33
	v_lshlrev_b32_e32 v32, 16, v31
	v_and_b32_e32 v33, 0xffff0000, v31
	v_sub_f32_e32 v32, v32, v50
	v_sub_f32_e32 v33, v33, v50
	v_mul_f32_e32 v32, v51, v32
	v_mul_f32_e32 v33, v51, v33
	ds_write_b128 v181, v[52:55] offset:51712
	v_cvt_pk_bf16_f32 v41, v41, v47
	v_fma_f32 v32, v34, v32, v38
	v_fmac_f32_e32 v39, v35, v33
	v_cvt_pk_bf16_f32 v43, v32, v39
	ds_write_b128 v183, v[40:43] offset:34816
	s_waitcnt lgkmcnt(0)
	s_barrier
	s_cbranch_scc1 .LBB0_292
	s_add_i32 s1, s0, s74
	s_mov_b64 s[72:73], 0

; template <int MODE> __device__ void phase_ln(const bf16_t* src, void* dst, const float* gam, const float* bet) {
;     const int lane = threadIdx.x & 63, wid = threadIdx.x >> 6;
;     for (int row = blockIdx.x * 8 + wid; row < T; row += gridDim.x * 8) {
;         float x[32];
; #pragma unroll
;         for (int it = 0; it < 4; ++it) { const u32x4 w = *(const u32x4*)(src + (size_t)row * DM + it * 512 + lane * 8);
;             x[it * 8 + 0] = bflo(w.x); x[it * 8 + 1] = bfhi(w.x); x[it * 8 + 2] = bflo(w.y); x[it * 8 + 3] = bfhi(w.y);
;             x[it * 8 + 4] = bflo(w.z); x[it * 8 + 5] = bfhi(w.z); x[it * 8 + 6] = bflo(w.w); x[it * 8 + 7] = bfhi(w.w); }
;         float s_ = 0.f;
; #pragma unroll
;         for (int i = 0; i < 32; ++i) s_ += x[i];
;         const float mu = wave_sum(s_) * (1.0f / DM);
;         float q = 0.f;
; #pragma unroll
;         for (int i = 0; i < 32; ++i) { x[i] -= mu; q += x[i] * x[i]; }
;         const float rs = rsqrtf(wave_sum(q) * (1.0f / DM) + 1e-5f);
; #pragma unroll
;         for (int it = 0; it < 4; ++it) {
;             const int col = it * 512 + lane * 8;
;             const f32x4 g0 = *(const f32x4*)(gam + col), g1 = *(const f32x4*)(gam + col + 4), b0 = *(const f32x4*)(bet + col), b1 = *(const f32x4*)(bet + col + 4);
.LBB0_989:
	v_lshrrev_b32_e32 v0, 6, v136
	v_lshl_add_u32 v0, s2, 3, v0
	s_mov_b32 s0, 0xa000
	v_cmp_gt_i32_e32 vcc, s0, v0
	s_and_saveexec_b64 s[0:1], vcc
	s_cbranch_execz .LBB0_992
	s_add_u32 s0, s48, 0x2000
	v_lshlrev_b32_e32 v1, 3, v136
	s_addc_u32 s1, s49, 0
	v_and_b32_e32 v22, 0x1f8, v1
	s_add_u32 s4, s46, 0x2000
	v_mov_b32_e32 v3, 0
	v_lshlrev_b32_e32 v2, 1, v22
	s_addc_u32 s5, s47, 0
	v_lshl_add_u64 v[4:5], s[26:27], 0, v[2:3]
	v_lshlrev_b32_e32 v2, 2, v22
	v_lshl_add_u64 v[6:7], s[4:5], 0, v[2:3]
	v_lshl_add_u64 v[8:9], s[0:1], 0, v[2:3]
	v_or_b32_e32 v2, 0x800, v2
	v_or_b32_e32 v24, 0x400, v22
	v_lshl_add_u64 v[10:11], s[4:5], 0, v[2:3]
	s_waitcnt lgkmcnt(0)
	v_lshl_add_u64 v[12:13], s[0:1], 0, v[2:3]
	v_lshlrev_b32_e32 v2, 2, v24
	v_or_b32_e32 v34, 0x600, v22
	v_mbcnt_lo_u32_b32 v1, -1, 0
	v_lshl_add_u64 v[14:15], s[4:5], 0, v[2:3]
	v_lshl_add_u64 v[16:17], s[0:1], 0, v[2:3]
	v_lshlrev_b32_e32 v2, 2, v34
	v_mbcnt_hi_u32_b32 v1, -1, v1
	v_lshl_add_u64 v[18:19], s[4:5], 0, v[2:3]
	v_lshl_add_u64 v[20:21], s[0:1], 0, v[2:3]
	v_and_b32_e32 v2, 64, v1
	v_add_u32_e32 v2, 64, v2
	v_xor_b32_e32 v23, 32, v1
	v_cmp_lt_i32_e32 vcc, v23, v2
	s_lshl_b32 s2, s30, 3
	s_mov_b64 s[0:1], 0
	v_cndmask_b32_e32 v23, v1, v23, vcc
	v_lshlrev_b32_e32 v26, 2, v23
	v_xor_b32_e32 v23, 16, v1
	v_cmp_lt_i32_e32 vcc, v23, v2
	v_mov_b32_e32 v32, 0x3727c5ac
	s_mov_b32 s3, 0x800000
	v_cndmask_b32_e32 v23, v1, v23, vcc
	v_lshlrev_b32_e32 v27, 2, v23
	v_xor_b32_e32 v23, 8, v1
	v_cmp_lt_i32_e32 vcc, v23, v2
	s_mov_b32 s4, 0x9fff
	v_mov_b32_e32 v25, v3
	v_cndmask_b32_e32 v23, v1, v23, vcc
	v_lshlrev_b32_e32 v28, 2, v23
	v_xor_b32_e32 v23, 4, v1
	v_cmp_lt_i32_e32 vcc, v23, v2
	s_nop 1
	v_cndmask_b32_e32 v23, v1, v23, vcc
	v_lshlrev_b32_e32 v29, 2, v23
	v_xor_b32_e32 v23, 2, v1
	v_cmp_lt_i32_e32 vcc, v23, v2
	s_nop 1
	v_cndmask_b32_e32 v23, v1, v23, vcc
	v_lshlrev_b32_e32 v30, 2, v23
	v_xor_b32_e32 v23, 1, v1
	v_cmp_lt_i32_e32 vcc, v23, v2
	v_lshlrev_b32_e32 v2, 2, v22
	v_lshlrev_b32_e32 v22, 2, v24
	v_cndmask_b32_e32 v1, v1, v23, vcc
	v_lshlrev_b32_e32 v31, 2, v1
	v_mov_b32_e32 v23, v3
	v_lshlrev_b32_e32 v24, 2, v34
	v_ashrrev_i32_e32 v1, 31, v0
	v_lshlrev_b64 v[34:35], 12, v[0:1]
	v_lshl_add_u64 v[50:51], v[4:5], 0, v[34:35]
	global_load_dwordx4 v[184:187], v[50:51], off
	global_load_dwordx4 v[188:191], v[50:51], off offset:1024
	global_load_dwordx4 v[192:195], v[50:51], off offset:2048
	global_load_dwordx4 v[196:199], v[50:51], off offset:3072
	global_load_dwordx4 v[120:123], v[6:7], off
	global_load_dwordx4 v[124:127], v[6:7], off offset:16
	global_load_dwordx4 v[128:131], v[8:9], off
	global_load_dwordx4 v[132:135], v[8:9], off offset:16
	global_load_dwordx4 v[136:139], v[10:11], off
	global_load_dwordx4 v[140:143], v[10:11], off offset:16
	global_load_dwordx4 v[144:147], v[12:13], off
	global_load_dwordx4 v[148:151], v[12:13], off offset:16
	global_load_dwordx4 v[152:155], v[14:15], off
	global_load_dwordx4 v[156:159], v[14:15], off offset:16
	global_load_dwordx4 v[160:163], v[16:17], off
	global_load_dwordx4 v[164:167], v[16:17], off offset:16
	global_load_dwordx4 v[168:171], v[18:19], off
	global_load_dwordx4 v[172:175], v[18:19], off offset:16
	global_load_dwordx4 v[176:179], v[20:21], off
	global_load_dwordx4 v[180:183], v[20:21], off offset:16
	s_waitcnt vmcnt(0)
.LBB0_991:
	s_waitcnt vmcnt(8)
	v_mov_b64 v[34:35], v[184:185]
	v_mov_b64 v[36:37], v[186:187]
	v_mov_b64 v[38:39], v[188:189]
	v_mov_b64 v[40:41], v[190:191]
	v_mov_b64 v[42:43], v[192:193]
	v_mov_b64 v[44:45], v[194:195]
	v_mov_b64 v[46:47], v[196:197]
	v_mov_b64 v[48:49], v[198:199]
	v_add_u32_e32 v200, s2, v0
	v_ashrrev_i32_e32 v201, 31, v200
	v_lshlrev_b64 v[200:201], 12, v[200:201]
	v_lshl_add_u64 v[200:201], v[4:5], 0, v[200:201]
	global_load_dwordx4 v[184:187], v[200:201], off
	global_load_dwordx4 v[188:191], v[200:201], off offset:1024
	global_load_dwordx4 v[192:195], v[200:201], off offset:2048
	global_load_dwordx4 v[196:199], v[200:201], off offset:3072
	v_ashrrev_i32_e32 v1, 31, v0
	v_lshlrev_b32_e32 v54, 16, v34
	v_and_b32_e32 v55, 0xffff0000, v34
	v_add_f32_e32 v33, 0, v54
	v_lshlrev_b32_e32 v56, 16, v35
	v_add_f32_e32 v33, v33, v55
	v_and_b32_e32 v57, 0xffff0000, v35
	v_add_f32_e32 v33, v33, v56
	v_lshlrev_b32_e32 v50, 16, v36
	v_add_f32_e32 v33, v33, v57
	v_and_b32_e32 v51, 0xffff0000, v36
	v_add_f32_e32 v33, v33, v50
	v_lshlrev_b32_e32 v52, 16, v37
	v_add_f32_e32 v33, v33, v51
	v_and_b32_e32 v53, 0xffff0000, v37
	v_add_f32_e32 v33, v33, v52
	v_lshlrev_b32_e32 v62, 16, v38
	v_add_f32_e32 v33, v33, v53
	v_and_b32_e32 v63, 0xffff0000, v38
	v_add_f32_e32 v33, v33, v62
	v_lshlrev_b32_e32 v64, 16, v39
	v_add_f32_e32 v33, v33, v63
	v_and_b32_e32 v65, 0xffff0000, v39
	v_add_f32_e32 v33, v33, v64
	v_lshlrev_b32_e32 v58, 16, v40
	v_add_f32_e32 v33, v33, v65
	v_and_b32_e32 v59, 0xffff0000, v40
	v_add_f32_e32 v33, v33, v58
	v_lshlrev_b32_e32 v60, 16, v41
	v_add_f32_e32 v33, v33, v59
	v_and_b32_e32 v61, 0xffff0000, v41
	v_add_f32_e32 v33, v33, v60
	v_lshlrev_b32_e32 v70, 16, v42
	v_add_f32_e32 v33, v33, v61
	v_and_b32_e32 v71, 0xffff0000, v42
	v_add_f32_e32 v33, v33, v70
	v_lshlrev_b32_e32 v72, 16, v43
	v_add_f32_e32 v33, v33, v71
	v_and_b32_e32 v73, 0xffff0000, v43
	v_add_f32_e32 v33, v33, v72
	v_lshlrev_b32_e32 v66, 16, v44
	v_add_f32_e32 v33, v33, v73
	v_and_b32_e32 v67, 0xffff0000, v44
	v_add_f32_e32 v33, v33, v66
	v_lshlrev_b32_e32 v68, 16, v45
	v_add_f32_e32 v33, v33, v67
	v_and_b32_e32 v69, 0xffff0000, v45
	v_add_f32_e32 v33, v33, v68
	v_lshlrev_b32_e32 v78, 16, v46
	v_add_f32_e32 v33, v33, v69
	v_and_b32_e32 v79, 0xffff0000, v46
	v_add_f32_e32 v33, v33, v78
	v_lshlrev_b32_e32 v80, 16, v47
	v_add_f32_e32 v33, v33, v79
	v_and_b32_e32 v81, 0xffff0000, v47
	v_add_f32_e32 v33, v33, v80
	v_lshlrev_b32_e32 v74, 16, v48
	v_add_f32_e32 v33, v33, v81
	v_and_b32_e32 v75, 0xffff0000, v48
	v_add_f32_e32 v33, v33, v74
	v_lshlrev_b32_e32 v76, 16, v49
	v_add_f32_e32 v33, v33, v75
	v_and_b32_e32 v77, 0xffff0000, v49
	v_add_f32_e32 v33, v33, v76
	v_add_f32_e32 v33, v33, v77
	ds_bpermute_b32 v34, v26, v33
	s_waitcnt lgkmcnt(0)
; DI unsigned cvt_pk_bf16(float lo, float hi) { unsigned r; asm("v_cvt_pk_bf16_f32 %0, %1, %2" : "=v"(r) : "v"(lo), "v"(hi)); return r; }
; template <int MODE> __device__ void phase_ln(const bf16_t* src, void* dst, const float* gam, const float* bet) {
;     ...
;         const float mu = wave_sum(s_) * (1.0f / DM);
;         float q = 0.f;
; #pragma unroll
;         for (int i = 0; i < 32; ++i) { x[i] -= mu; q += x[i] * x[i]; }
;         const float rs = rsqrtf(wave_sum(q) * (1.0f / DM) + 1e-5f);
; #pragma unroll
;         for (int it = 0; it < 4; ++it) {
;             const int col = it * 512 + lane * 8;
;             const f32x4 g0 = *(const f32x4*)(gam + col), g1 = *(const f32x4*)(gam + col + 4), b0 = *(const f32x4*)(bet + col), b1 = *(const f32x4*)(bet + col + 4);
;             f32x4 y0, y1;
; #pragma unroll
;             for (int j = 0; j < 4; ++j) { y0[j] = x[it * 8 + j] * rs * g0[j] + b0[j]; y1[j] = x[it * 8 + 4 + j] * rs * g1[j] + b1[j]; }
;             if (MODE == 1) { float* o = (float*)dst + (size_t)row * DM + col; *(f32x4*)o = y0; *(f32x4*)(o + 4) = y1; }
;             else { u32x4 w; w.x = cvt_pk_bf16(y0[0], y0[1]); w.y = cvt_pk_bf16(y0[2], y0[3]); w.z = cvt_pk_bf16(y1[0], y1[1]); w.w = cvt_pk_bf16(y1[2], y1[3]);
;                    *(u32x4*)((bf16_t*)dst + (size_t)row * DM + col) = w; }
;         }
	v_add_f32_e32 v33, v33, v34
	ds_bpermute_b32 v34, v27, v33
	s_waitcnt lgkmcnt(0)
	v_add_f32_e32 v33, v33, v34
	ds_bpermute_b32 v34, v28, v33
	s_waitcnt lgkmcnt(0)
	v_add_f32_e32 v33, v33, v34
	ds_bpermute_b32 v34, v29, v33
	s_waitcnt lgkmcnt(0)
	v_add_f32_e32 v33, v33, v34
	ds_bpermute_b32 v34, v30, v33
	s_waitcnt lgkmcnt(0)
	v_add_f32_e32 v33, v33, v34
	ds_bpermute_b32 v82, v31, v33
	s_waitcnt lgkmcnt(0)
	v_add_f32_e32 v33, v33, v82
	v_mul_f32_e32 v82, 0x3a000000, v33
	v_pk_add_f32 v[54:55], v[54:55], v[82:83] op_sel_hi:[1,0] neg_lo:[0,1] neg_hi:[0,1]
	v_pk_add_f32 v[56:57], v[56:57], v[82:83] op_sel_hi:[1,0] neg_lo:[0,1] neg_hi:[0,1]
	v_pk_add_f32 v[50:51], v[50:51], v[82:83] op_sel_hi:[1,0] neg_lo:[0,1] neg_hi:[0,1]
	v_pk_add_f32 v[52:53], v[52:53], v[82:83] op_sel_hi:[1,0] neg_lo:[0,1] neg_hi:[0,1]
	v_pk_add_f32 v[62:63], v[62:63], v[82:83] op_sel_hi:[1,0] neg_lo:[0,1] neg_hi:[0,1]
	v_pk_add_f32 v[64:65], v[64:65], v[82:83] op_sel_hi:[1,0] neg_lo:[0,1] neg_hi:[0,1]
	v_pk_add_f32 v[58:59], v[58:59], v[82:83] op_sel_hi:[1,0] neg_lo:[0,1] neg_hi:[0,1]
	v_pk_add_f32 v[60:61], v[60:61], v[82:83] op_sel_hi:[1,0] neg_lo:[0,1] neg_hi:[0,1]
	v_pk_add_f32 v[70:71], v[70:71], v[82:83] op_sel_hi:[1,0] neg_lo:[0,1] neg_hi:[0,1]
	v_pk_add_f32 v[72:73], v[72:73], v[82:83] op_sel_hi:[1,0] neg_lo:[0,1] neg_hi:[0,1]
	v_pk_add_f32 v[66:67], v[66:67], v[82:83] op_sel_hi:[1,0] neg_lo:[0,1] neg_hi:[0,1]
	v_pk_add_f32 v[68:69], v[68:69], v[82:83] op_sel_hi:[1,0] neg_lo:[0,1] neg_hi:[0,1]
	v_pk_add_f32 v[78:79], v[78:79], v[82:83] op_sel_hi:[1,0] neg_lo:[0,1] neg_hi:[0,1]
	v_pk_add_f32 v[80:81], v[80:81], v[82:83] op_sel_hi:[1,0] neg_lo:[0,1] neg_hi:[0,1]
	v_pk_add_f32 v[74:75], v[74:75], v[82:83] op_sel_hi:[1,0] neg_lo:[0,1] neg_hi:[0,1]
	v_pk_add_f32 v[76:77], v[76:77], v[82:83] op_sel_hi:[1,0] neg_lo:[0,1] neg_hi:[0,1]
	v_pk_mul_f32 v[82:83], v[54:55], v[54:55]
	v_pk_mul_f32 v[84:85], v[56:57], v[56:57]
	v_add_f32_e32 v33, v82, v83
	v_add_f32_e32 v33, v84, v33
	v_pk_mul_f32 v[86:87], v[50:51], v[50:51]
	v_add_f32_e32 v33, v85, v33
	v_add_f32_e32 v33, v86, v33
	v_pk_mul_f32 v[88:89], v[52:53], v[52:53]
	v_add_f32_e32 v33, v87, v33
	v_add_f32_e32 v33, v88, v33
	v_pk_mul_f32 v[90:91], v[62:63], v[62:63]
	v_add_f32_e32 v33, v89, v33
	v_add_f32_e32 v33, v90, v33
	v_pk_mul_f32 v[92:93], v[64:65], v[64:65]
	v_add_f32_e32 v33, v91, v33
	v_add_f32_e32 v33, v92, v33
	v_pk_mul_f32 v[94:95], v[58:59], v[58:59]
	v_add_f32_e32 v33, v93, v33
	v_add_f32_e32 v33, v94, v33
	v_pk_mul_f32 v[96:97], v[60:61], v[60:61]
	v_add_f32_e32 v33, v95, v33
	v_add_f32_e32 v33, v96, v33
	v_pk_mul_f32 v[98:99], v[70:71], v[70:71]
	v_add_f32_e32 v33, v97, v33
	v_add_f32_e32 v33, v98, v33
	v_pk_mul_f32 v[100:101], v[72:73], v[72:73]
	v_add_f32_e32 v33, v99, v33
	v_add_f32_e32 v33, v100, v33
	v_pk_mul_f32 v[102:103], v[66:67], v[66:67]
	v_add_f32_e32 v33, v101, v33
	v_add_f32_e32 v33, v102, v33
	v_pk_mul_f32 v[104:105], v[68:69], v[68:69]
	v_add_f32_e32 v33, v103, v33
	v_add_f32_e32 v33, v104, v33
	v_pk_mul_f32 v[106:107], v[78:79], v[78:79]
	v_add_f32_e32 v33, v105, v33
	v_add_f32_e32 v33, v106, v33
	v_pk_mul_f32 v[108:109], v[80:81], v[80:81]
	v_add_f32_e32 v33, v107, v33
	v_add_f32_e32 v33, v108, v33
	v_pk_mul_f32 v[110:111], v[74:75], v[74:75]
	v_add_f32_e32 v33, v109, v33
	v_add_f32_e32 v33, v110, v33
	v_pk_mul_f32 v[112:113], v[76:77], v[76:77]
	v_add_f32_e32 v33, v111, v33
	v_add_f32_e32 v33, v112, v33
	v_add_f32_e32 v33, v113, v33
	ds_bpermute_b32 v82, v26, v33
	s_waitcnt lgkmcnt(0)
	v_add_f32_e32 v33, v33, v82
	ds_bpermute_b32 v82, v27, v33
	s_waitcnt lgkmcnt(0)
	v_add_f32_e32 v33, v33, v82
	ds_bpermute_b32 v82, v28, v33
	s_waitcnt lgkmcnt(0)
	v_add_f32_e32 v33, v33, v82
	ds_bpermute_b32 v82, v29, v33
	s_waitcnt lgkmcnt(0)
	v_add_f32_e32 v33, v33, v82
	ds_bpermute_b32 v82, v30, v33
	s_waitcnt lgkmcnt(0)
	v_add_f32_e32 v33, v33, v82
	ds_bpermute_b32 v82, v31, v33
	s_waitcnt lgkmcnt(0)
	v_add_f32_e32 v33, v33, v82
	v_fmamk_f32 v33, v33, 0x3a000000, v32
	v_mul_f32_e32 v82, 0x4b800000, v33
	v_cmp_gt_f32_e32 vcc, s3, v33
	s_nop 1
	v_cndmask_b32_e32 v33, v33, v82, vcc
	v_rsq_f32_e32 v33, v33
	v_lshlrev_b64 v[82:83], 13, v[0:1]
	v_lshl_add_u64 v[82:83], s[50:51], 0, v[82:83]
	v_lshl_add_u64 v[84:85], v[82:83], 0, v[2:3]
	v_mul_f32_e32 v1, 0x45800000, v33
	v_cndmask_b32_e32 v86, v33, v1, vcc
	v_pk_mul_f32 v[54:55], v[54:55], v[86:87] op_sel_hi:[1,0]
	v_pk_mul_f32 v[56:57], v[56:57], v[86:87] op_sel_hi:[1,0]
	v_pk_mul_f32 v[50:51], v[50:51], v[86:87] op_sel_hi:[1,0]
	v_pk_mul_f32 v[52:53], v[52:53], v[86:87] op_sel_hi:[1,0]
	v_pk_fma_f32 v[38:39], v[120:121], v[54:55], v[128:129]
	v_pk_fma_f32 v[40:41], v[122:123], v[56:57], v[130:131]
	v_pk_fma_f32 v[34:35], v[124:125], v[50:51], v[132:133]
	v_pk_fma_f32 v[36:37], v[126:127], v[52:53], v[134:135]
	global_store_dwordx4 v[84:85], v[38:41], off
	global_store_dwordx4 v[84:85], v[34:37], off offset:16
	v_pk_mul_f32 v[50:51], v[64:65], v[86:87] op_sel_hi:[1,0]
	v_pk_mul_f32 v[52:53], v[62:63], v[86:87] op_sel_hi:[1,0]
	v_pk_mul_f32 v[54:55], v[60:61], v[86:87] op_sel_hi:[1,0]
	v_pk_mul_f32 v[56:57], v[58:59], v[86:87] op_sel_hi:[1,0]
	v_add_u32_e32 v0, s2, v0
	v_cmp_lt_i32_e32 vcc, s4, v0
	s_or_b64 s[0:1], vcc, s[0:1]
	v_pk_fma_f32 v[42:43], v[136:137], v[52:53], v[144:145]
	v_pk_fma_f32 v[44:45], v[138:139], v[50:51], v[146:147]
	v_pk_fma_f32 v[46:47], v[140:141], v[56:57], v[148:149]
	v_pk_fma_f32 v[48:49], v[142:143], v[54:55], v[150:151]
	global_store_dwordx4 v[84:85], v[42:45], off offset:2048
	global_store_dwordx4 v[84:85], v[46:49], off offset:2064
	v_pk_mul_f32 v[54:55], v[70:71], v[86:87] op_sel_hi:[1,0]
	v_pk_mul_f32 v[52:53], v[72:73], v[86:87] op_sel_hi:[1,0]
	v_pk_mul_f32 v[58:59], v[66:67], v[86:87] op_sel_hi:[1,0]
	v_pk_mul_f32 v[56:57], v[68:69], v[86:87] op_sel_hi:[1,0]
	v_lshl_add_u64 v[50:51], v[82:83], 0, v[22:23]
	v_pk_fma_f32 v[34:35], v[152:153], v[54:55], v[160:161]
	v_pk_fma_f32 v[36:37], v[154:155], v[52:53], v[162:163]
	v_pk_fma_f32 v[38:39], v[156:157], v[58:59], v[164:165]
	v_pk_fma_f32 v[40:41], v[158:159], v[56:57], v[166:167]
	global_store_dwordx4 v[50:51], v[34:37], off
	global_store_dwordx4 v[50:51], v[38:41], off offset:16
	v_pk_mul_f32 v[54:55], v[78:79], v[86:87] op_sel_hi:[1,0]
	v_pk_mul_f32 v[52:53], v[80:81], v[86:87] op_sel_hi:[1,0]
	v_pk_mul_f32 v[58:59], v[74:75], v[86:87] op_sel_hi:[1,0]
	v_pk_mul_f32 v[56:57], v[76:77], v[86:87] op_sel_hi:[1,0]
	v_lshl_add_u64 v[50:51], v[82:83], 0, v[24:25]
	v_pk_fma_f32 v[42:43], v[168:169], v[54:55], v[176:177]
	v_pk_fma_f32 v[44:45], v[170:171], v[52:53], v[178:179]
	v_pk_fma_f32 v[46:47], v[172:173], v[58:59], v[180:181]
	v_pk_fma_f32 v[48:49], v[174:175], v[56:57], v[182:183]
	global_store_dwordx4 v[50:51], v[42:45], off
	global_store_dwordx4 v[50:51], v[46:49], off offset:16
	s_andn2_b64 exec, exec, s[0:1]
	s_cbranch_execnz .LBB0_991

; #define LAS __attribute__((address_space(3)))
; __global__ void __launch_bounds__(512) fwd_megakernel(Params p) {
;     extern __shared__ __attribute__((aligned(16))) unsigned char shm[];
;     cg::grid_group grid = cg::this_grid();
;     LAS unsigned char* lds = (LAS unsigned char*)shm;
;     pg8::StaticOrder S;
;     if (p.ph_hi > 1000) grid.sync();
;     if (threadIdx.x < 2) ((volatile LAS unsigned*)(lds + 157696))[threadIdx.x] = 0u;
;     __syncthreads();
;     XcdBarrier xb = xcd_barrier_post((unsigned*)(p.ws + OFF_SINK), (volatile LAS unsigned*)(lds + 157696));
	.amdhsa_kernel _Z14fwd_megakernel6Params
		.amdhsa_group_segment_fixed_size 0
		.amdhsa_private_segment_fixed_size 0
		.amdhsa_kernarg_size 400
		.amdhsa_user_sgpr_count 2
		.amdhsa_user_sgpr_dispatch_ptr 0
		.amdhsa_user_sgpr_queue_ptr 0
		.amdhsa_user_sgpr_kernarg_segment_ptr 1
		.amdhsa_user_sgpr_dispatch_id 0
		.amdhsa_user_sgpr_kernarg_preload_length 0
		.amdhsa_user_sgpr_kernarg_preload_offset 0
		.amdhsa_user_sgpr_private_segment_size 0
		.amdhsa_uses_dynamic_stack 0
		.amdhsa_enable_private_segment 0
		.amdhsa_system_sgpr_workgroup_id_x 1
		.amdhsa_system_sgpr_workgroup_id_y 0
		.amdhsa_system_sgpr_workgroup_id_z 0
		.amdhsa_system_sgpr_workgroup_info 0
		.amdhsa_system_vgpr_workitem_id 2
		.amdhsa_next_free_vgpr 256
		.amdhsa_next_free_sgpr 102
		.amdhsa_accum_offset 256
		.amdhsa_reserve_vcc 1
		.amdhsa_float_round_mode_32 0
		.amdhsa_float_round_mode_16_64 0
		.amdhsa_float_denorm_mode_32 3
		.amdhsa_float_denorm_mode_16_64 3
		.amdhsa_dx10_clamp 1
		.amdhsa_ieee_mode 1
		.amdhsa_fp16_overflow 0
		.amdhsa_tg_split 0
		.amdhsa_exception_fp_ieee_invalid_op 0
		.amdhsa_exception_fp_denorm_src 0
		.amdhsa_exception_fp_ieee_div_zero 0
		.amdhsa_exception_fp_ieee_overflow 0
		.amdhsa_exception_fp_ieee_underflow 0
		.amdhsa_exception_fp_ieee_inexact 0
		.amdhsa_exception_int_div_zero 0
	.end_amdhsa_kernel

; #define LAS __attribute__((address_space(3)))
; __global__ void __launch_bounds__(512) fwd_megakernel(Params p) {
;     extern __shared__ __attribute__((aligned(16))) unsigned char shm[];
;     cg::grid_group grid = cg::this_grid();
;     LAS unsigned char* lds = (LAS unsigned char*)shm;
;     pg8::StaticOrder S;
;     if (p.ph_hi > 1000) grid.sync();
;     if (threadIdx.x < 2) ((volatile LAS unsigned*)(lds + 157696))[threadIdx.x] = 0u;
;     __syncthreads();
;     XcdBarrier xb = xcd_barrier_post((unsigned*)(p.ws + OFF_SINK), (volatile LAS unsigned*)(lds + 157696));
amdhsa.kernels:
  - .agpr_count:     0
    .args:
      - .offset:         0
        .size:           144
        .value_kind:     by_value
      - .offset:         144
        .size:           4
        .value_kind:     hidden_block_count_x
      - .offset:         148
        .size:           4
        .value_kind:     hidden_block_count_y
      - .offset:         152
        .size:           4
        .value_kind:     hidden_block_count_z
      - .offset:         156
        .size:           2
        .value_kind:     hidden_group_size_x
      - .offset:         158
        .size:           2
        .value_kind:     hidden_group_size_y
      - .offset:         160
        .size:           2
        .value_kind:     hidden_group_size_z
      - .offset:         162
        .size:           2
        .value_kind:     hidden_remainder_x
      - .offset:         164
        .size:           2
        .value_kind:     hidden_remainder_y
      - .offset:         166
        .size:           2
        .value_kind:     hidden_remainder_z
      - .offset:         184
        .size:           8
        .value_kind:     hidden_global_offset_x
      - .offset:         192
        .size:           8
        .value_kind:     hidden_global_offset_y
      - .offset:         200
        .size:           8
        .value_kind:     hidden_global_offset_z
      - .offset:         208
        .size:           2
        .value_kind:     hidden_grid_dims
      - .offset:         232
        .size:           8
        .value_kind:     hidden_multigrid_sync_arg
      - .offset:         264
        .size:           4
        .value_kind:     hidden_dynamic_lds_size
    .group_segment_fixed_size: 0
    .kernarg_segment_align: 8
    .kernarg_segment_size: 400
    .language:       OpenCL C
    .language_version:
      - 2
      - 0
    .max_flat_workgroup_size: 512
    .name:           _Z14fwd_megakernel6Params
    .private_segment_fixed_size: 0
    .sgpr_count:     108
    .sgpr_spill_count: 10
    .symbol:         _Z14fwd_megakernel6Params.kd
    .uniform_work_group_size: 1
    .uses_dynamic_stack: false
    .vgpr_count:     256
    .vgpr_spill_count: 0
    .wavefront_size: 64
